# MLA_Q epilogue: per-row PART loads hoisted 4 rows ahead, counted vmcnt (KV variant dropped: no gain in the phase-repeat experiment)
# baseline (speedup 1.0000x reference)
; __device__ __forceinline__ unsigned cvt_pk_bf16(float lo, float hi) { unsigned r; asm volatile("v_cvt_pk_bf16_f32 %0, %1, %2" : "=v"(r) : "v"(lo), "v"(hi)); return r; }
; __device__ __forceinline__ u32x4 pack8(f32x4 a, f32x4 b) { u32x4 w; w.x = cvt_pk_bf16(a[0], a[1]); w.y = cvt_pk_bf16(a[2], a[3]); w.z = cvt_pk_bf16(b[0], b[1]); w.w = cvt_pk_bf16(b[2], b[3]); return w; }
;     __device__ __forceinline__ void operator()(const f32x4 (&acc)[2][2][4][2], const pg8::Unit& u, int wr, int wc, int fr, int fq) const {
;     ...
;                 for (int m = 0; m < 4; ++m) { const int row = row0 + ai * 128 + m * 16;
;                     const f32x4 pa = *(const f32x4*)(f0 + (size_t)row * 16), pb = *(const f32x4*)(f0 + (size_t)row * 16 + 4);
;                     const float ssq = ((pa[0] + pa[1]) + (pa[2] + pa[3])) + ((pb[0] + pb[1]) + (pb[2] + pb[3]));
;                     const float sc = qsc / sqrtf(ssq * (1.0f / 512.0f) + 1e-6f);
; #pragma unroll
;                     for (int bj = 0; bj < 2; ++bj) { const int col = colb + bj * 128; const f32x4 v0 = acc[ai][bj][m][0] * sc, v1 = acc[ai][bj][m][1] * sc;
;                         if (pn < 8) { const int h = col >> 7, d = col & 127; *(u32x4*)(o0 + (size_t)row * 3072 + h * 192 + d) = pack8(v0, v1); }
;                         else { const int j = col - 2048, h = j >> 6, i0 = (j & 63) >> 1, pos = row & 8191;
;                             const f32x4 t0 = *(const f32x4*)(tab + ((size_t)pos * 32 + i0) * 2), t1 = *(const f32x4*)(tab + ((size_t)pos * 32 + i0) * 2 + 4);
;                             const float a0 = v0[0] * t0[0] - v0[1] * t0[1], b0 = v0[1] * t0[0] + v0[0] * t0[1];
;                             const float a1 = v0[2] * t0[2] - v0[3] * t0[3], b1 = v0[3] * t0[2] + v0[2] * t0[3];
;                             const float a2 = v1[0] * t1[0] - v1[1] * t1[1], b2 = v1[1] * t1[0] + v1[0] * t1[1];
;                             const float a3 = v1[2] * t1[2] - v1[3] * t1[3], b3 = v1[3] * t1[2] + v1[2] * t1[3];
;                             u32x2 wa, wb; wa.x = cvt_pk_bf16(a0, a1); wa.y = cvt_pk_bf16(a2, a3); wb.x = cvt_pk_bf16(b0, b1); wb.y = cvt_pk_bf16(b2, b3);
;                             bf16_t* qp = o0 + (size_t)row * 3072 + h * 192 + 128 + i0; *(u32x2*)qp = wa; *(u32x2*)(qp + 32) = wb; } }
.LBB0_746:
	s_andn2_b64 vcc, exec, s[18:19]
	s_cbranch_vccnz .LBB0_812
	v_lshrrev_b32_e32 v128, 1, v156
	v_ashrrev_i32_e32 v159, 31, v158
	v_and_b32_e32 v155, 28, v128
	v_lshlrev_b64 v[128:129], 6, v[158:159]
	v_lshlrev_b32_e32 v178, 6, v158
	v_add_u32_e32 v179, 0x2000, v178
	global_load_dwordx4 v[190:193], v178, s[50:51]
	global_load_dwordx4 v[194:197], v178, s[50:51] offset:16
	global_load_dwordx4 v[198:201], v178, s[50:51] offset:1024
	global_load_dwordx4 v[202:205], v178, s[50:51] offset:1040
	global_load_dwordx4 v[224:227], v178, s[50:51] offset:2048
	global_load_dwordx4 v[228:231], v178, s[50:51] offset:2064
	global_load_dwordx4 v[232:235], v178, s[50:51] offset:3072
	global_load_dwordx4 v[236:239], v178, s[50:51] offset:3088
	s_mov_b32 s23, 0x3dd53b94
	s_cmp_gt_i32 s4, 7
	s_cselect_b64 s[20:21], -1, 0
	s_waitcnt vmcnt(6)
	v_mov_b32_e32 v128, v190
	v_mov_b32_e32 v129, v191
	v_mov_b32_e32 v130, v192
	v_mov_b32_e32 v131, v193
	v_mov_b32_e32 v132, v194
	v_mov_b32_e32 v133, v195
	v_mov_b32_e32 v134, v196
	v_mov_b32_e32 v135, v197
	global_load_dwordx4 v[190:193], v179, s[50:51]
	global_load_dwordx4 v[194:197], v179, s[50:51] offset:16
	v_mov_b32_e32 v136, v128
	v_mov_b32_e32 v137, v132
	v_mov_b32_e32 v132, v129
	v_pk_add_f32 v[128:129], v[136:137], v[132:133]
	v_mov_b32_e32 v132, v130
	v_mov_b32_e32 v133, v134
	v_mov_b32_e32 v134, v131
	v_pk_add_f32 v[130:131], v[132:133], v[134:135]
	s_nop 0
	v_pk_add_f32 v[128:129], v[128:129], v[130:131]
	s_nop 0
	v_add_f32_e32 v128, v128, v129
	v_fmamk_f32 v128, v128, 0x3b000000, v219
	v_cmp_gt_f32_e32 vcc, s86, v128
	v_mul_f32_e32 v129, 0x4f800000, v128
	s_nop 0
	v_cndmask_b32_e32 v128, v128, v129, vcc
	v_sqrt_f32_e32 v129, v128
	s_nop 0
	v_add_u32_e32 v130, -1, v129
	v_fma_f32 v131, -v130, v129, v128
	v_cmp_ge_f32_e64 s[44:45], 0, v131
	v_add_u32_e32 v131, 1, v129
	s_nop 0
	v_cndmask_b32_e64 v130, v129, v130, s[44:45]
	v_fma_f32 v129, -v131, v129, v128
	v_cmp_lt_f32_e64 s[44:45], 0, v129
	s_nop 1
	v_cndmask_b32_e64 v129, v130, v131, s[44:45]
	v_mul_f32_e32 v130, 0x37800000, v129
	v_cndmask_b32_e32 v129, v129, v130, vcc
	v_cmp_class_f32_e32 vcc, v128, v215
	s_nop 1
	v_cndmask_b32_e32 v128, v129, v128, vcc
	v_div_scale_f32 v129, s[18:19], v128, v128, s23
	v_rcp_f32_e32 v130, v129
	s_mov_b32 s18, 0x3f9e0
	v_fma_f32 v131, -v129, v130, 1.0
	v_fmac_f32_e32 v130, v131, v130
	v_div_scale_f32 v131, vcc, s23, v128, s23
	v_mul_f32_e32 v132, v131, v130
	v_fma_f32 v133, -v129, v132, v131
	v_fmac_f32_e32 v132, v133, v130
	v_fma_f32 v129, -v129, v132, v131
	v_div_fmas_f32 v129, v129, v130, v132
	v_div_fixup_f32 v130, v129, v128, s23
	v_lshlrev_b32_e32 v128, 5, v158
	v_and_or_b32 v128, v128, s18, v155
	s_movk_i32 s18, 0x1800
	v_lshlrev_b32_e32 v131, 1, v128
	v_mad_i64_i32 v[128:129], s[18:19], v158, s18, 0
	v_pk_mul_f32 v[136:137], v[126:127], v[130:131] op_sel_hi:[1,0]
	v_pk_mul_f32 v[162:163], v[124:125], v[130:131] op_sel_hi:[1,0]
	v_pk_mul_f32 v[134:135], v[122:123], v[130:131] op_sel_hi:[1,0]
	v_pk_mul_f32 v[160:161], v[120:121], v[130:131] op_sel_hi:[1,0]
	s_mov_b64 s[18:19], -1
	s_and_b64 vcc, exec, s[20:21]
	v_lshl_add_u64 v[132:133], s[94:95], 0, v[128:129]
	v_lshlrev_b32_e32 v157, 2, v131
	v_lshlrev_b32_e32 v128, 1, v155
	s_cbranch_vccz .LBB0_749
	global_load_dwordx4 v[164:167], v157, s[72:73] offset:16
	global_load_dwordx4 v[168:171], v157, s[72:73]
	s_add_i32 s18, s22, 0xfffff800
	s_lshr_b32 s18, s18, 6
	s_mulk_i32 s18, 0xc0
	s_ashr_i32 s19, s18, 31
	s_waitcnt vmcnt(0)
	v_pk_mul_f32 v[174:175], v[162:163], v[168:169]
	v_pk_mul_f32 v[168:169], v[162:163], v[168:169] op_sel:[1,0] op_sel_hi:[0,1]
	v_pk_mul_f32 v[172:173], v[136:137], v[170:171]
	v_add_f32_e32 v131, v168, v169
	v_pk_mul_f32 v[168:169], v[136:137], v[170:171] op_sel:[1,0] op_sel_hi:[0,1]
	v_sub_f32_e32 v159, v172, v173
	v_add_f32_e32 v172, v168, v169
	v_pk_mul_f32 v[168:169], v[134:135], v[166:167]
	v_pk_mul_f32 v[170:171], v[160:161], v[164:165]
	v_pk_mul_f32 v[164:165], v[160:161], v[164:165] op_sel:[1,0] op_sel_hi:[0,1]
	v_sub_f32_e32 v129, v174, v175
	v_sub_f32_e32 v170, v170, v171
	v_add_f32_e32 v171, v164, v165
	v_sub_f32_e32 v168, v168, v169
	v_pk_mul_f32 v[164:165], v[134:135], v[166:167] op_sel:[1,0] op_sel_hi:[0,1]
	v_add_f32_e32 v167, v164, v165
	v_cvt_pk_bf16_f32 v164, v129, v159
	v_cvt_pk_bf16_f32 v165, v170, v168
	v_lshl_add_u64 v[168:169], s[18:19], 1, v[132:133]
	v_mov_b32_e32 v129, v181
	v_lshl_add_u64 v[168:169], v[168:169], 0, v[128:129]
	v_cvt_pk_bf16_f32 v166, v131, v172
	v_cvt_pk_bf16_f32 v167, v171, v167
	global_store_dwordx2 v[168:169], v[164:165], off offset:256
	global_store_dwordx2 v[168:169], v[166:167], off offset:320
	s_mov_b64 s[18:19], 0

; __device__ __forceinline__ unsigned cvt_pk_bf16(float lo, float hi) { unsigned r; asm volatile("v_cvt_pk_bf16_f32 %0, %1, %2" : "=v"(r) : "v"(lo), "v"(hi)); return r; }
; __device__ __forceinline__ u32x4 pack8(f32x4 a, f32x4 b) { u32x4 w; w.x = cvt_pk_bf16(a[0], a[1]); w.y = cvt_pk_bf16(a[2], a[3]); w.z = cvt_pk_bf16(b[0], b[1]); w.w = cvt_pk_bf16(b[2], b[3]); return w; }
;     __device__ __forceinline__ void operator()(const f32x4 (&acc)[2][2][4][2], const pg8::Unit& u, int wr, int wc, int fr, int fq) const {
;     ...
;                 for (int m = 0; m < 4; ++m) { const int row = row0 + ai * 128 + m * 16;
;                     const f32x4 pa = *(const f32x4*)(f0 + (size_t)row * 16), pb = *(const f32x4*)(f0 + (size_t)row * 16 + 4);
;                     const float ssq = ((pa[0] + pa[1]) + (pa[2] + pa[3])) + ((pb[0] + pb[1]) + (pb[2] + pb[3]));
;                     const float sc = qsc / sqrtf(ssq * (1.0f / 512.0f) + 1e-6f);
; #pragma unroll
;                     for (int bj = 0; bj < 2; ++bj) { const int col = colb + bj * 128; const f32x4 v0 = acc[ai][bj][m][0] * sc, v1 = acc[ai][bj][m][1] * sc;
;                         if (pn < 8) { const int h = col >> 7, d = col & 127; *(u32x4*)(o0 + (size_t)row * 3072 + h * 192 + d) = pack8(v0, v1); }
;                         else { const int j = col - 2048, h = j >> 6, i0 = (j & 63) >> 1, pos = row & 8191;
;                             const f32x4 t0 = *(const f32x4*)(tab + ((size_t)pos * 32 + i0) * 2), t1 = *(const f32x4*)(tab + ((size_t)pos * 32 + i0) * 2 + 4);
;                             const float a0 = v0[0] * t0[0] - v0[1] * t0[1], b0 = v0[1] * t0[0] + v0[0] * t0[1];
;                             const float a1 = v0[2] * t0[2] - v0[3] * t0[3], b1 = v0[3] * t0[2] + v0[2] * t0[3];
;                             const float a2 = v1[0] * t1[0] - v1[1] * t1[1], b2 = v1[1] * t1[0] + v1[0] * t1[1];
;                             const float a3 = v1[2] * t1[2] - v1[3] * t1[3], b3 = v1[3] * t1[2] + v1[2] * t1[3];
;                             u32x2 wa, wb; wa.x = cvt_pk_bf16(a0, a1); wa.y = cvt_pk_bf16(a2, a3); wb.x = cvt_pk_bf16(b0, b1); wb.y = cvt_pk_bf16(b2, b3);
;                             bf16_t* qp = o0 + (size_t)row * 3072 + h * 192 + 128 + i0; *(u32x2*)qp = wa; *(u32x2*)(qp + 32) = wb; } }
.LBB0_755:
	v_or_b32_e32 v136, 16, v158
	v_ashrrev_i32_e32 v137, 31, v136
	v_lshlrev_b64 v[132:133], 6, v[136:137]
	s_mov_b32 s19, 0x3dd53b94
	s_waitcnt vmcnt(8)
	v_mov_b32_e32 v132, v198
	v_mov_b32_e32 v133, v199
	v_mov_b32_e32 v134, v200
	v_mov_b32_e32 v135, v201
	v_mov_b32_e32 v160, v202
	v_mov_b32_e32 v161, v203
	v_mov_b32_e32 v162, v204
	v_mov_b32_e32 v163, v205
	global_load_dwordx4 v[198:201], v179, s[50:51] offset:1024
	global_load_dwordx4 v[202:205], v179, s[50:51] offset:1040
	v_mov_b32_e32 v164, v132
	v_mov_b32_e32 v165, v160
	v_mov_b32_e32 v160, v133
	v_pk_add_f32 v[132:133], v[164:165], v[160:161]
	v_mov_b32_e32 v160, v134
	v_mov_b32_e32 v161, v162
	v_mov_b32_e32 v162, v135
	v_pk_add_f32 v[134:135], v[160:161], v[162:163]
	s_nop 0
	v_pk_add_f32 v[132:133], v[132:133], v[134:135]
	s_nop 0
	v_add_f32_e32 v129, v132, v133
	v_fmamk_f32 v129, v129, 0x3b000000, v219
	v_cmp_gt_f32_e32 vcc, s86, v129
	v_mul_f32_e32 v131, 0x4f800000, v129
	s_nop 0
	v_cndmask_b32_e32 v129, v129, v131, vcc
	v_sqrt_f32_e32 v131, v129
	s_nop 0
	v_add_u32_e32 v132, -1, v131
	v_fma_f32 v133, -v132, v131, v129
	v_cmp_ge_f32_e64 s[46:47], 0, v133
	v_add_u32_e32 v133, 1, v131
	s_nop 0
	v_cndmask_b32_e64 v132, v131, v132, s[46:47]
	v_fma_f32 v131, -v133, v131, v129
	v_cmp_lt_f32_e64 s[46:47], 0, v131
	s_nop 1
	v_cndmask_b32_e64 v131, v132, v133, s[46:47]
	v_mul_f32_e32 v132, 0x37800000, v131
	v_cndmask_b32_e32 v131, v131, v132, vcc
	v_cmp_class_f32_e32 vcc, v129, v215
	s_nop 1
	v_cndmask_b32_e32 v129, v131, v129, vcc
	v_div_scale_f32 v131, s[20:21], v129, v129, s19
	v_rcp_f32_e32 v132, v131
	s_nop 0
	v_fma_f32 v133, -v131, v132, 1.0
	v_fmac_f32_e32 v132, v133, v132
	v_div_scale_f32 v133, vcc, s19, v129, s19
	v_mul_f32_e32 v134, v133, v132
	v_fma_f32 v135, -v131, v134, v133
	v_fmac_f32_e32 v134, v135, v132
	v_fma_f32 v131, -v131, v134, v133
	v_div_fmas_f32 v131, v131, v132, v134
	v_div_fixup_f32 v134, v131, v129, s19
	v_lshlrev_b32_e32 v129, 5, v136
	s_mov_b32 s19, 0x3fbe0
	v_and_or_b32 v129, v129, s19, v155
	s_movk_i32 s19, 0x1800
	v_lshlrev_b32_e32 v129, 1, v129
	v_mad_i64_i32 v[132:133], s[20:21], v136, s19, 0
	v_pk_mul_f32 v[160:161], v[110:111], v[134:135] op_sel_hi:[1,0]
	v_pk_mul_f32 v[164:165], v[108:109], v[134:135] op_sel_hi:[1,0]
	v_pk_mul_f32 v[136:137], v[106:107], v[134:135] op_sel_hi:[1,0]
	v_pk_mul_f32 v[162:163], v[104:105], v[134:135] op_sel_hi:[1,0]
	s_mov_b64 s[20:21], -1
	s_and_b64 vcc, exec, s[44:45]
	v_lshl_add_u64 v[132:133], s[94:95], 0, v[132:133]
	v_lshlrev_b32_e32 v131, 2, v129
	s_cbranch_vccnz .LBB0_757
	global_load_dwordx4 v[166:169], v131, s[72:73] offset:16
	global_load_dwordx4 v[170:173], v131, s[72:73]
	s_add_i32 s19, s22, 0xfffff800
	s_lshr_b32 s19, s19, 6
	s_mul_i32 s20, s19, 0xc0
	s_ashr_i32 s21, s20, 31
	s_waitcnt vmcnt(0)
	v_pk_mul_f32 v[176:177], v[164:165], v[170:171]
	v_pk_mul_f32 v[170:171], v[164:165], v[170:171] op_sel:[1,0] op_sel_hi:[0,1]
	v_add_f32_e32 v135, v170, v171
	v_pk_mul_f32 v[170:171], v[160:161], v[172:173] op_sel:[1,0] op_sel_hi:[0,1]
	v_pk_mul_f32 v[174:175], v[160:161], v[172:173]
	v_add_f32_e32 v159, v170, v171
	v_pk_mul_f32 v[170:171], v[136:137], v[168:169]
	v_pk_mul_f32 v[172:173], v[162:163], v[166:167]
	v_pk_mul_f32 v[166:167], v[162:163], v[166:167] op_sel:[1,0] op_sel_hi:[0,1]
	v_sub_f32_e32 v129, v176, v177
	v_sub_f32_e32 v172, v172, v173
	v_add_f32_e32 v173, v166, v167
	v_sub_f32_e32 v170, v170, v171
	v_pk_mul_f32 v[166:167], v[136:137], v[168:169] op_sel:[1,0] op_sel_hi:[0,1]
	v_sub_f32_e32 v157, v174, v175
	v_add_f32_e32 v169, v166, v167
	v_cvt_pk_bf16_f32 v166, v129, v157
	v_cvt_pk_bf16_f32 v167, v172, v170
	v_lshl_add_u64 v[170:171], s[20:21], 1, v[132:133]
	v_mov_b32_e32 v129, v181
	v_lshl_add_u64 v[170:171], v[170:171], 0, v[128:129]
	s_mov_b64 s[20:21], 0
	v_cvt_pk_bf16_f32 v168, v135, v159
	v_cvt_pk_bf16_f32 v169, v173, v169
	global_store_dwordx2 v[170:171], v[166:167], off offset:256
	global_store_dwordx2 v[170:171], v[168:169], off offset:320

; __device__ __forceinline__ unsigned cvt_pk_bf16(float lo, float hi) { unsigned r; asm volatile("v_cvt_pk_bf16_f32 %0, %1, %2" : "=v"(r) : "v"(lo), "v"(hi)); return r; }
; __device__ __forceinline__ u32x4 pack8(f32x4 a, f32x4 b) { u32x4 w; w.x = cvt_pk_bf16(a[0], a[1]); w.y = cvt_pk_bf16(a[2], a[3]); w.z = cvt_pk_bf16(b[0], b[1]); w.w = cvt_pk_bf16(b[2], b[3]); return w; }
;     __device__ __forceinline__ void operator()(const f32x4 (&acc)[2][2][4][2], const pg8::Unit& u, int wr, int wc, int fr, int fq) const {
;     ...
;                 for (int m = 0; m < 4; ++m) { const int row = row0 + ai * 128 + m * 16;
;                     const f32x4 pa = *(const f32x4*)(f0 + (size_t)row * 16), pb = *(const f32x4*)(f0 + (size_t)row * 16 + 4);
;                     const float ssq = ((pa[0] + pa[1]) + (pa[2] + pa[3])) + ((pb[0] + pb[1]) + (pb[2] + pb[3]));
;                     const float sc = qsc / sqrtf(ssq * (1.0f / 512.0f) + 1e-6f);
; #pragma unroll
;                     for (int bj = 0; bj < 2; ++bj) { const int col = colb + bj * 128; const f32x4 v0 = acc[ai][bj][m][0] * sc, v1 = acc[ai][bj][m][1] * sc;
;                         if (pn < 8) { const int h = col >> 7, d = col & 127; *(u32x4*)(o0 + (size_t)row * 3072 + h * 192 + d) = pack8(v0, v1); }
;                         else { const int j = col - 2048, h = j >> 6, i0 = (j & 63) >> 1, pos = row & 8191;
;                             const f32x4 t0 = *(const f32x4*)(tab + ((size_t)pos * 32 + i0) * 2), t1 = *(const f32x4*)(tab + ((size_t)pos * 32 + i0) * 2 + 4);
;                             const float a0 = v0[0] * t0[0] - v0[1] * t0[1], b0 = v0[1] * t0[0] + v0[0] * t0[1];
;                             const float a1 = v0[2] * t0[2] - v0[3] * t0[3], b1 = v0[3] * t0[2] + v0[2] * t0[3];
;                             const float a2 = v1[0] * t1[0] - v1[1] * t1[1], b2 = v1[1] * t1[0] + v1[0] * t1[1];
;                             const float a3 = v1[2] * t1[2] - v1[3] * t1[3], b3 = v1[3] * t1[2] + v1[2] * t1[3];
;                             u32x2 wa, wb; wa.x = cvt_pk_bf16(a0, a1); wa.y = cvt_pk_bf16(a2, a3); wb.x = cvt_pk_bf16(b0, b1); wb.y = cvt_pk_bf16(b2, b3);
;                             bf16_t* qp = o0 + (size_t)row * 3072 + h * 192 + 128 + i0; *(u32x2*)qp = wa; *(u32x2*)(qp + 32) = wb; } }
.LBB0_763:
	v_or_b32_e32 v136, 32, v158
	v_ashrrev_i32_e32 v137, 31, v136
	v_lshlrev_b64 v[132:133], 6, v[136:137]
	s_mov_b32 s19, 0x3dd53b94
	s_waitcnt vmcnt(10)
	v_mov_b32_e32 v132, v224
	v_mov_b32_e32 v133, v225
	v_mov_b32_e32 v134, v226
	v_mov_b32_e32 v135, v227
	v_mov_b32_e32 v160, v228
	v_mov_b32_e32 v161, v229
	v_mov_b32_e32 v162, v230
	v_mov_b32_e32 v163, v231
	global_load_dwordx4 v[224:227], v179, s[50:51] offset:2048
	global_load_dwordx4 v[228:231], v179, s[50:51] offset:2064
	v_mov_b32_e32 v164, v132
	v_mov_b32_e32 v165, v160
	v_mov_b32_e32 v160, v133
	v_pk_add_f32 v[132:133], v[164:165], v[160:161]
	v_mov_b32_e32 v160, v134
	v_mov_b32_e32 v161, v162
	v_mov_b32_e32 v162, v135
	v_pk_add_f32 v[134:135], v[160:161], v[162:163]
	s_nop 0
	v_pk_add_f32 v[132:133], v[132:133], v[134:135]
	s_nop 0
	v_add_f32_e32 v129, v132, v133
	v_fmamk_f32 v129, v129, 0x3b000000, v219
	v_cmp_gt_f32_e32 vcc, s86, v129
	v_mul_f32_e32 v131, 0x4f800000, v129
	s_nop 0
	v_cndmask_b32_e32 v129, v129, v131, vcc
	v_sqrt_f32_e32 v131, v129
	s_nop 0
	v_add_u32_e32 v132, -1, v131
	v_fma_f32 v133, -v132, v131, v129
	v_cmp_ge_f32_e64 s[46:47], 0, v133
	v_add_u32_e32 v133, 1, v131
	s_nop 0
	v_cndmask_b32_e64 v132, v131, v132, s[46:47]
	v_fma_f32 v131, -v133, v131, v129
	v_cmp_lt_f32_e64 s[46:47], 0, v131
	s_nop 1
	v_cndmask_b32_e64 v131, v132, v133, s[46:47]
	v_mul_f32_e32 v132, 0x37800000, v131
	v_cndmask_b32_e32 v131, v131, v132, vcc
	v_cmp_class_f32_e32 vcc, v129, v215
	s_nop 1
	v_cndmask_b32_e32 v129, v131, v129, vcc
	v_div_scale_f32 v131, s[20:21], v129, v129, s19
	v_rcp_f32_e32 v132, v131
	s_nop 0
	v_fma_f32 v133, -v131, v132, 1.0
	v_fmac_f32_e32 v132, v133, v132
	v_div_scale_f32 v133, vcc, s19, v129, s19
	v_mul_f32_e32 v134, v133, v132
	v_fma_f32 v135, -v131, v134, v133
	v_fmac_f32_e32 v134, v135, v132
	v_fma_f32 v131, -v131, v134, v133
	v_div_fmas_f32 v131, v131, v132, v134
	v_div_fixup_f32 v134, v131, v129, s19
	v_lshlrev_b32_e32 v129, 5, v136
	s_mov_b32 s19, 0x3fde0
	v_and_or_b32 v129, v129, s19, v155
	s_movk_i32 s19, 0x1800
	v_lshlrev_b32_e32 v129, 1, v129
	v_mad_i64_i32 v[132:133], s[20:21], v136, s19, 0
	v_pk_mul_f32 v[160:161], v[94:95], v[134:135] op_sel_hi:[1,0]
	v_pk_mul_f32 v[164:165], v[92:93], v[134:135] op_sel_hi:[1,0]
	v_pk_mul_f32 v[136:137], v[90:91], v[134:135] op_sel_hi:[1,0]
	v_pk_mul_f32 v[162:163], v[88:89], v[134:135] op_sel_hi:[1,0]
	s_mov_b64 s[20:21], -1
	s_and_b64 vcc, exec, s[44:45]
	v_lshl_add_u64 v[132:133], s[94:95], 0, v[132:133]
	v_lshlrev_b32_e32 v131, 2, v129
	s_cbranch_vccnz .LBB0_765
	global_load_dwordx4 v[166:169], v131, s[72:73] offset:16
	global_load_dwordx4 v[170:173], v131, s[72:73]
	s_add_i32 s19, s22, 0xfffff800
	s_lshr_b32 s19, s19, 6
	s_mul_i32 s20, s19, 0xc0
	s_ashr_i32 s21, s20, 31
	s_waitcnt vmcnt(0)
	v_pk_mul_f32 v[176:177], v[164:165], v[170:171]
	v_pk_mul_f32 v[170:171], v[164:165], v[170:171] op_sel:[1,0] op_sel_hi:[0,1]
	v_add_f32_e32 v135, v170, v171
	v_pk_mul_f32 v[170:171], v[160:161], v[172:173] op_sel:[1,0] op_sel_hi:[0,1]
	v_pk_mul_f32 v[174:175], v[160:161], v[172:173]
	v_add_f32_e32 v159, v170, v171
	v_pk_mul_f32 v[170:171], v[136:137], v[168:169]
	v_pk_mul_f32 v[172:173], v[162:163], v[166:167]
	v_pk_mul_f32 v[166:167], v[162:163], v[166:167] op_sel:[1,0] op_sel_hi:[0,1]
	v_sub_f32_e32 v129, v176, v177
	v_sub_f32_e32 v172, v172, v173
	v_add_f32_e32 v173, v166, v167
	v_sub_f32_e32 v170, v170, v171
	v_pk_mul_f32 v[166:167], v[136:137], v[168:169] op_sel:[1,0] op_sel_hi:[0,1]
	v_sub_f32_e32 v157, v174, v175
	v_add_f32_e32 v169, v166, v167
	v_cvt_pk_bf16_f32 v166, v129, v157
	v_cvt_pk_bf16_f32 v167, v172, v170
	v_lshl_add_u64 v[170:171], s[20:21], 1, v[132:133]
	v_mov_b32_e32 v129, v181
	v_lshl_add_u64 v[170:171], v[170:171], 0, v[128:129]
	s_mov_b64 s[20:21], 0
	v_cvt_pk_bf16_f32 v168, v135, v159
	v_cvt_pk_bf16_f32 v169, v173, v169
	global_store_dwordx2 v[170:171], v[166:167], off offset:256
	global_store_dwordx2 v[170:171], v[168:169], off offset:320

; __device__ __forceinline__ unsigned cvt_pk_bf16(float lo, float hi) { unsigned r; asm volatile("v_cvt_pk_bf16_f32 %0, %1, %2" : "=v"(r) : "v"(lo), "v"(hi)); return r; }
; __device__ __forceinline__ u32x4 pack8(f32x4 a, f32x4 b) { u32x4 w; w.x = cvt_pk_bf16(a[0], a[1]); w.y = cvt_pk_bf16(a[2], a[3]); w.z = cvt_pk_bf16(b[0], b[1]); w.w = cvt_pk_bf16(b[2], b[3]); return w; }
;     __device__ __forceinline__ void operator()(const f32x4 (&acc)[2][2][4][2], const pg8::Unit& u, int wr, int wc, int fr, int fq) const {
;     ...
;                 for (int m = 0; m < 4; ++m) { const int row = row0 + ai * 128 + m * 16;
;                     const f32x4 pa = *(const f32x4*)(f0 + (size_t)row * 16), pb = *(const f32x4*)(f0 + (size_t)row * 16 + 4);
;                     const float ssq = ((pa[0] + pa[1]) + (pa[2] + pa[3])) + ((pb[0] + pb[1]) + (pb[2] + pb[3]));
;                     const float sc = qsc / sqrtf(ssq * (1.0f / 512.0f) + 1e-6f);
; #pragma unroll
;                     for (int bj = 0; bj < 2; ++bj) { const int col = colb + bj * 128; const f32x4 v0 = acc[ai][bj][m][0] * sc, v1 = acc[ai][bj][m][1] * sc;
;                         if (pn < 8) { const int h = col >> 7, d = col & 127; *(u32x4*)(o0 + (size_t)row * 3072 + h * 192 + d) = pack8(v0, v1); }
;                         else { const int j = col - 2048, h = j >> 6, i0 = (j & 63) >> 1, pos = row & 8191;
;                             const f32x4 t0 = *(const f32x4*)(tab + ((size_t)pos * 32 + i0) * 2), t1 = *(const f32x4*)(tab + ((size_t)pos * 32 + i0) * 2 + 4);
;                             const float a0 = v0[0] * t0[0] - v0[1] * t0[1], b0 = v0[1] * t0[0] + v0[0] * t0[1];
;                             const float a1 = v0[2] * t0[2] - v0[3] * t0[3], b1 = v0[3] * t0[2] + v0[2] * t0[3];
;                             const float a2 = v1[0] * t1[0] - v1[1] * t1[1], b2 = v1[1] * t1[0] + v1[0] * t1[1];
;                             const float a3 = v1[2] * t1[2] - v1[3] * t1[3], b3 = v1[3] * t1[2] + v1[2] * t1[3];
;                             u32x2 wa, wb; wa.x = cvt_pk_bf16(a0, a1); wa.y = cvt_pk_bf16(a2, a3); wb.x = cvt_pk_bf16(b0, b1); wb.y = cvt_pk_bf16(b2, b3);
;                             bf16_t* qp = o0 + (size_t)row * 3072 + h * 192 + 128 + i0; *(u32x2*)qp = wa; *(u32x2*)(qp + 32) = wb; } }
.LBB0_771:
	v_or_b32_e32 v136, 48, v158
	v_ashrrev_i32_e32 v137, 31, v136
	v_lshlrev_b64 v[132:133], 6, v[136:137]
	s_mov_b32 s19, 0x3dd53b94
	s_waitcnt vmcnt(12)
	v_mov_b32_e32 v132, v232
	v_mov_b32_e32 v133, v233
	v_mov_b32_e32 v134, v234
	v_mov_b32_e32 v135, v235
	v_mov_b32_e32 v160, v236
	v_mov_b32_e32 v161, v237
	v_mov_b32_e32 v162, v238
	v_mov_b32_e32 v163, v239
	global_load_dwordx4 v[232:235], v179, s[50:51] offset:3072
	global_load_dwordx4 v[236:239], v179, s[50:51] offset:3088
	v_mov_b32_e32 v164, v132
	v_mov_b32_e32 v165, v160
	v_mov_b32_e32 v160, v133
	v_pk_add_f32 v[132:133], v[164:165], v[160:161]
	v_mov_b32_e32 v160, v134
	v_mov_b32_e32 v161, v162
	v_mov_b32_e32 v162, v135
	v_pk_add_f32 v[134:135], v[160:161], v[162:163]
	s_nop 0
	v_pk_add_f32 v[132:133], v[132:133], v[134:135]
	s_nop 0
	v_add_f32_e32 v129, v132, v133
	v_fmamk_f32 v129, v129, 0x3b000000, v219
	v_cmp_gt_f32_e32 vcc, s86, v129
	v_mul_f32_e32 v131, 0x4f800000, v129
	s_nop 0
	v_cndmask_b32_e32 v129, v129, v131, vcc
	v_sqrt_f32_e32 v131, v129
	s_nop 0
	v_add_u32_e32 v132, -1, v131
	v_fma_f32 v133, -v132, v131, v129
	v_cmp_ge_f32_e64 s[46:47], 0, v133
	v_add_u32_e32 v133, 1, v131
	s_nop 0
	v_cndmask_b32_e64 v132, v131, v132, s[46:47]
	v_fma_f32 v131, -v133, v131, v129
	v_cmp_lt_f32_e64 s[46:47], 0, v131
	s_nop 1
	v_cndmask_b32_e64 v131, v132, v133, s[46:47]
	v_mul_f32_e32 v132, 0x37800000, v131
	v_cndmask_b32_e32 v131, v131, v132, vcc
	v_cmp_class_f32_e32 vcc, v129, v215
	s_nop 1
	v_cndmask_b32_e32 v129, v131, v129, vcc
	v_div_scale_f32 v131, s[20:21], v129, v129, s19
	v_rcp_f32_e32 v132, v131
	s_nop 0
	v_fma_f32 v133, -v131, v132, 1.0
	v_fmac_f32_e32 v132, v133, v132
	v_div_scale_f32 v133, vcc, s19, v129, s19
	v_mul_f32_e32 v134, v133, v132
	v_fma_f32 v135, -v131, v134, v133
	v_fmac_f32_e32 v134, v135, v132
	v_fma_f32 v131, -v131, v134, v133
	v_div_fmas_f32 v131, v131, v132, v134
	v_div_fixup_f32 v134, v131, v129, s19
	v_lshlrev_b32_e32 v129, 5, v136
	s_mov_b32 s19, 0x3ffe0
	v_and_or_b32 v129, v129, s19, v155
	s_movk_i32 s19, 0x1800
	v_lshlrev_b32_e32 v129, 1, v129
	v_mad_i64_i32 v[132:133], s[20:21], v136, s19, 0
	v_pk_mul_f32 v[160:161], v[78:79], v[134:135] op_sel_hi:[1,0]
	v_pk_mul_f32 v[164:165], v[76:77], v[134:135] op_sel_hi:[1,0]
	v_pk_mul_f32 v[136:137], v[74:75], v[134:135] op_sel_hi:[1,0]
	v_pk_mul_f32 v[162:163], v[72:73], v[134:135] op_sel_hi:[1,0]
	s_mov_b64 s[20:21], -1
	s_and_b64 vcc, exec, s[44:45]
	v_lshl_add_u64 v[132:133], s[94:95], 0, v[132:133]
	v_lshlrev_b32_e32 v131, 2, v129
	s_cbranch_vccnz .LBB0_773
	global_load_dwordx4 v[166:169], v131, s[72:73] offset:16
	global_load_dwordx4 v[170:173], v131, s[72:73]
	s_add_i32 s19, s22, 0xfffff800
	s_lshr_b32 s19, s19, 6
	s_mul_i32 s20, s19, 0xc0
	s_ashr_i32 s21, s20, 31
	s_waitcnt vmcnt(0)
	v_pk_mul_f32 v[176:177], v[164:165], v[170:171]
	v_pk_mul_f32 v[170:171], v[164:165], v[170:171] op_sel:[1,0] op_sel_hi:[0,1]
	v_add_f32_e32 v135, v170, v171
	v_pk_mul_f32 v[170:171], v[160:161], v[172:173] op_sel:[1,0] op_sel_hi:[0,1]
	v_pk_mul_f32 v[174:175], v[160:161], v[172:173]
	v_add_f32_e32 v159, v170, v171
	v_pk_mul_f32 v[170:171], v[136:137], v[168:169]
	v_pk_mul_f32 v[172:173], v[162:163], v[166:167]
	v_pk_mul_f32 v[166:167], v[162:163], v[166:167] op_sel:[1,0] op_sel_hi:[0,1]
	v_sub_f32_e32 v129, v176, v177
	v_sub_f32_e32 v172, v172, v173
	v_add_f32_e32 v173, v166, v167
	v_sub_f32_e32 v170, v170, v171
	v_pk_mul_f32 v[166:167], v[136:137], v[168:169] op_sel:[1,0] op_sel_hi:[0,1]
	v_sub_f32_e32 v157, v174, v175
	v_add_f32_e32 v169, v166, v167
	v_cvt_pk_bf16_f32 v166, v129, v157
	v_cvt_pk_bf16_f32 v167, v172, v170
	v_lshl_add_u64 v[170:171], s[20:21], 1, v[132:133]
	v_mov_b32_e32 v129, v181
	v_lshl_add_u64 v[170:171], v[170:171], 0, v[128:129]
	s_mov_b64 s[20:21], 0
	v_cvt_pk_bf16_f32 v168, v135, v159
	v_cvt_pk_bf16_f32 v169, v173, v169
	global_store_dwordx2 v[170:171], v[166:167], off offset:256
	global_store_dwordx2 v[170:171], v[168:169], off offset:320

; __device__ __forceinline__ unsigned cvt_pk_bf16(float lo, float hi) { unsigned r; asm volatile("v_cvt_pk_bf16_f32 %0, %1, %2" : "=v"(r) : "v"(lo), "v"(hi)); return r; }
; __device__ __forceinline__ u32x4 pack8(f32x4 a, f32x4 b) { u32x4 w; w.x = cvt_pk_bf16(a[0], a[1]); w.y = cvt_pk_bf16(a[2], a[3]); w.z = cvt_pk_bf16(b[0], b[1]); w.w = cvt_pk_bf16(b[2], b[3]); return w; }
;     __device__ __forceinline__ void operator()(const f32x4 (&acc)[2][2][4][2], const pg8::Unit& u, int wr, int wc, int fr, int fq) const {
;     ...
;                 for (int m = 0; m < 4; ++m) { const int row = row0 + ai * 128 + m * 16;
;                     const f32x4 pa = *(const f32x4*)(f0 + (size_t)row * 16), pb = *(const f32x4*)(f0 + (size_t)row * 16 + 4);
;                     const float ssq = ((pa[0] + pa[1]) + (pa[2] + pa[3])) + ((pb[0] + pb[1]) + (pb[2] + pb[3]));
;                     const float sc = qsc / sqrtf(ssq * (1.0f / 512.0f) + 1e-6f);
; #pragma unroll
;                     for (int bj = 0; bj < 2; ++bj) { const int col = colb + bj * 128; const f32x4 v0 = acc[ai][bj][m][0] * sc, v1 = acc[ai][bj][m][1] * sc;
;                         if (pn < 8) { const int h = col >> 7, d = col & 127; *(u32x4*)(o0 + (size_t)row * 3072 + h * 192 + d) = pack8(v0, v1); }
;                         else { const int j = col - 2048, h = j >> 6, i0 = (j & 63) >> 1, pos = row & 8191;
;                             const f32x4 t0 = *(const f32x4*)(tab + ((size_t)pos * 32 + i0) * 2), t1 = *(const f32x4*)(tab + ((size_t)pos * 32 + i0) * 2 + 4);
;                             const float a0 = v0[0] * t0[0] - v0[1] * t0[1], b0 = v0[1] * t0[0] + v0[0] * t0[1];
;                             const float a1 = v0[2] * t0[2] - v0[3] * t0[3], b1 = v0[3] * t0[2] + v0[2] * t0[3];
;                             const float a2 = v1[0] * t1[0] - v1[1] * t1[1], b2 = v1[1] * t1[0] + v1[0] * t1[1];
;                             const float a3 = v1[2] * t1[2] - v1[3] * t1[3], b3 = v1[3] * t1[2] + v1[2] * t1[3];
;                             u32x2 wa, wb; wa.x = cvt_pk_bf16(a0, a1); wa.y = cvt_pk_bf16(a2, a3); wb.x = cvt_pk_bf16(b0, b1); wb.y = cvt_pk_bf16(b2, b3);
;                             bf16_t* qp = o0 + (size_t)row * 3072 + h * 192 + 128 + i0; *(u32x2*)qp = wa; *(u32x2*)(qp + 32) = wb; } }
.LBB0_779:
	v_add_u32_e32 v136, 0x80, v158
	v_ashrrev_i32_e32 v137, 31, v136
	v_lshlrev_b64 v[132:133], 6, v[136:137]
	s_mov_b32 s19, 0x3dd53b94
	s_waitcnt vmcnt(14)
	v_mov_b32_e32 v132, v190
	v_mov_b32_e32 v133, v191
	v_mov_b32_e32 v134, v192
	v_mov_b32_e32 v135, v193
	v_mov_b32_e32 v160, v194
	v_mov_b32_e32 v161, v195
	v_mov_b32_e32 v162, v196
	v_mov_b32_e32 v163, v197
	v_mov_b32_e32 v164, v132
	v_mov_b32_e32 v165, v160
	v_mov_b32_e32 v160, v133
	v_pk_add_f32 v[132:133], v[164:165], v[160:161]
	v_mov_b32_e32 v160, v134
	v_mov_b32_e32 v161, v162
	v_mov_b32_e32 v162, v135
	v_pk_add_f32 v[134:135], v[160:161], v[162:163]
	s_nop 0
	v_pk_add_f32 v[132:133], v[132:133], v[134:135]
	s_nop 0
	v_add_f32_e32 v129, v132, v133
	v_fmamk_f32 v129, v129, 0x3b000000, v219
	v_cmp_gt_f32_e32 vcc, s86, v129
	v_mul_f32_e32 v131, 0x4f800000, v129
	s_nop 0
	v_cndmask_b32_e32 v129, v129, v131, vcc
	v_sqrt_f32_e32 v131, v129
	s_nop 0
	v_add_u32_e32 v132, -1, v131
	v_fma_f32 v133, -v132, v131, v129
	v_cmp_ge_f32_e64 s[46:47], 0, v133
	v_add_u32_e32 v133, 1, v131
	s_nop 0
	v_cndmask_b32_e64 v132, v131, v132, s[46:47]
	v_fma_f32 v131, -v133, v131, v129
	v_cmp_lt_f32_e64 s[46:47], 0, v131
	s_nop 1
	v_cndmask_b32_e64 v131, v132, v133, s[46:47]
	v_mul_f32_e32 v132, 0x37800000, v131
	v_cndmask_b32_e32 v131, v131, v132, vcc
	v_cmp_class_f32_e32 vcc, v129, v215
	s_nop 1
	v_cndmask_b32_e32 v129, v131, v129, vcc
	v_div_scale_f32 v131, s[20:21], v129, v129, s19
	v_rcp_f32_e32 v132, v131
	s_nop 0
	v_fma_f32 v133, -v131, v132, 1.0
	v_fmac_f32_e32 v132, v133, v132
	v_div_scale_f32 v133, vcc, s19, v129, s19
	v_mul_f32_e32 v134, v133, v132
	v_fma_f32 v135, -v131, v134, v133
	v_fmac_f32_e32 v134, v135, v132
	v_fma_f32 v131, -v131, v134, v133
	v_div_fmas_f32 v131, v131, v132, v134
	v_div_fixup_f32 v134, v131, v129, s19
	v_lshlrev_b32_e32 v129, 5, v136
	s_mov_b32 s19, 0x3f9e0
	v_and_or_b32 v129, v129, s19, v155
	s_movk_i32 s19, 0x1800
	v_lshlrev_b32_e32 v129, 1, v129
	v_mad_i64_i32 v[132:133], s[20:21], v136, s19, 0
	v_pk_mul_f32 v[160:161], v[62:63], v[134:135] op_sel_hi:[1,0]
	v_pk_mul_f32 v[164:165], v[60:61], v[134:135] op_sel_hi:[1,0]
	v_pk_mul_f32 v[136:137], v[58:59], v[134:135] op_sel_hi:[1,0]
	v_pk_mul_f32 v[162:163], v[56:57], v[134:135] op_sel_hi:[1,0]
	s_mov_b64 s[20:21], -1
	s_and_b64 vcc, exec, s[44:45]
	v_lshl_add_u64 v[132:133], s[94:95], 0, v[132:133]
	v_lshlrev_b32_e32 v131, 2, v129
	s_cbranch_vccnz .LBB0_781
	global_load_dwordx4 v[166:169], v131, s[72:73] offset:16
	global_load_dwordx4 v[170:173], v131, s[72:73]
	s_add_i32 s19, s22, 0xfffff800
	s_lshr_b32 s19, s19, 6
	s_mul_i32 s20, s19, 0xc0
	s_ashr_i32 s21, s20, 31
	s_waitcnt vmcnt(0)
	v_pk_mul_f32 v[176:177], v[164:165], v[170:171]
	v_pk_mul_f32 v[170:171], v[164:165], v[170:171] op_sel:[1,0] op_sel_hi:[0,1]
	v_add_f32_e32 v135, v170, v171
	v_pk_mul_f32 v[170:171], v[160:161], v[172:173] op_sel:[1,0] op_sel_hi:[0,1]
	v_pk_mul_f32 v[174:175], v[160:161], v[172:173]
	v_add_f32_e32 v159, v170, v171
	v_pk_mul_f32 v[170:171], v[136:137], v[168:169]
	v_pk_mul_f32 v[172:173], v[162:163], v[166:167]
	v_pk_mul_f32 v[166:167], v[162:163], v[166:167] op_sel:[1,0] op_sel_hi:[0,1]
	v_sub_f32_e32 v129, v176, v177
	v_sub_f32_e32 v172, v172, v173
	v_add_f32_e32 v173, v166, v167
	v_sub_f32_e32 v170, v170, v171
	v_pk_mul_f32 v[166:167], v[136:137], v[168:169] op_sel:[1,0] op_sel_hi:[0,1]
	v_sub_f32_e32 v157, v174, v175
	v_add_f32_e32 v169, v166, v167
	v_cvt_pk_bf16_f32 v166, v129, v157
	v_cvt_pk_bf16_f32 v167, v172, v170
	v_lshl_add_u64 v[170:171], s[20:21], 1, v[132:133]
	v_mov_b32_e32 v129, v181
	v_lshl_add_u64 v[170:171], v[170:171], 0, v[128:129]
	s_mov_b64 s[20:21], 0
	v_cvt_pk_bf16_f32 v168, v135, v159
	v_cvt_pk_bf16_f32 v169, v173, v169
	global_store_dwordx2 v[170:171], v[166:167], off offset:256
	global_store_dwordx2 v[170:171], v[168:169], off offset:320

; __device__ __forceinline__ unsigned cvt_pk_bf16(float lo, float hi) { unsigned r; asm volatile("v_cvt_pk_bf16_f32 %0, %1, %2" : "=v"(r) : "v"(lo), "v"(hi)); return r; }
; __device__ __forceinline__ u32x4 pack8(f32x4 a, f32x4 b) { u32x4 w; w.x = cvt_pk_bf16(a[0], a[1]); w.y = cvt_pk_bf16(a[2], a[3]); w.z = cvt_pk_bf16(b[0], b[1]); w.w = cvt_pk_bf16(b[2], b[3]); return w; }
;     __device__ __forceinline__ void operator()(const f32x4 (&acc)[2][2][4][2], const pg8::Unit& u, int wr, int wc, int fr, int fq) const {
;     ...
;                 for (int m = 0; m < 4; ++m) { const int row = row0 + ai * 128 + m * 16;
;                     const f32x4 pa = *(const f32x4*)(f0 + (size_t)row * 16), pb = *(const f32x4*)(f0 + (size_t)row * 16 + 4);
;                     const float ssq = ((pa[0] + pa[1]) + (pa[2] + pa[3])) + ((pb[0] + pb[1]) + (pb[2] + pb[3]));
;                     const float sc = qsc / sqrtf(ssq * (1.0f / 512.0f) + 1e-6f);
; #pragma unroll
;                     for (int bj = 0; bj < 2; ++bj) { const int col = colb + bj * 128; const f32x4 v0 = acc[ai][bj][m][0] * sc, v1 = acc[ai][bj][m][1] * sc;
;                         if (pn < 8) { const int h = col >> 7, d = col & 127; *(u32x4*)(o0 + (size_t)row * 3072 + h * 192 + d) = pack8(v0, v1); }
;                         else { const int j = col - 2048, h = j >> 6, i0 = (j & 63) >> 1, pos = row & 8191;
;                             const f32x4 t0 = *(const f32x4*)(tab + ((size_t)pos * 32 + i0) * 2), t1 = *(const f32x4*)(tab + ((size_t)pos * 32 + i0) * 2 + 4);
;                             const float a0 = v0[0] * t0[0] - v0[1] * t0[1], b0 = v0[1] * t0[0] + v0[0] * t0[1];
;                             const float a1 = v0[2] * t0[2] - v0[3] * t0[3], b1 = v0[3] * t0[2] + v0[2] * t0[3];
;                             const float a2 = v1[0] * t1[0] - v1[1] * t1[1], b2 = v1[1] * t1[0] + v1[0] * t1[1];
;                             const float a3 = v1[2] * t1[2] - v1[3] * t1[3], b3 = v1[3] * t1[2] + v1[2] * t1[3];
;                             u32x2 wa, wb; wa.x = cvt_pk_bf16(a0, a1); wa.y = cvt_pk_bf16(a2, a3); wb.x = cvt_pk_bf16(b0, b1); wb.y = cvt_pk_bf16(b2, b3);
;                             bf16_t* qp = o0 + (size_t)row * 3072 + h * 192 + 128 + i0; *(u32x2*)qp = wa; *(u32x2*)(qp + 32) = wb; } }
.LBB0_787:
	v_add_u32_e32 v136, 0x90, v158
	v_ashrrev_i32_e32 v137, 31, v136
	v_lshlrev_b64 v[132:133], 6, v[136:137]
	s_mov_b32 s19, 0x3dd53b94
	s_waitcnt vmcnt(12)
	v_mov_b32_e32 v132, v198
	v_mov_b32_e32 v133, v199
	v_mov_b32_e32 v134, v200
	v_mov_b32_e32 v135, v201
	v_mov_b32_e32 v160, v202
	v_mov_b32_e32 v161, v203
	v_mov_b32_e32 v162, v204
	v_mov_b32_e32 v163, v205
	v_mov_b32_e32 v164, v132
	v_mov_b32_e32 v165, v160
	v_mov_b32_e32 v160, v133
	v_pk_add_f32 v[132:133], v[164:165], v[160:161]
	v_mov_b32_e32 v160, v134
	v_mov_b32_e32 v161, v162
	v_mov_b32_e32 v162, v135
	v_pk_add_f32 v[134:135], v[160:161], v[162:163]
	s_nop 0
	v_pk_add_f32 v[132:133], v[132:133], v[134:135]
	s_nop 0
	v_add_f32_e32 v129, v132, v133
	v_fmamk_f32 v129, v129, 0x3b000000, v219
	v_cmp_gt_f32_e32 vcc, s86, v129
	v_mul_f32_e32 v131, 0x4f800000, v129
	s_nop 0
	v_cndmask_b32_e32 v129, v129, v131, vcc
	v_sqrt_f32_e32 v131, v129
	s_nop 0
	v_add_u32_e32 v132, -1, v131
	v_fma_f32 v133, -v132, v131, v129
	v_cmp_ge_f32_e64 s[46:47], 0, v133
	v_add_u32_e32 v133, 1, v131
	s_nop 0
	v_cndmask_b32_e64 v132, v131, v132, s[46:47]
	v_fma_f32 v131, -v133, v131, v129
	v_cmp_lt_f32_e64 s[46:47], 0, v131
	s_nop 1
	v_cndmask_b32_e64 v131, v132, v133, s[46:47]
	v_mul_f32_e32 v132, 0x37800000, v131
	v_cndmask_b32_e32 v131, v131, v132, vcc
	v_cmp_class_f32_e32 vcc, v129, v215
	s_nop 1
	v_cndmask_b32_e32 v129, v131, v129, vcc
	v_div_scale_f32 v131, s[20:21], v129, v129, s19
	v_rcp_f32_e32 v132, v131
	s_nop 0
	v_fma_f32 v133, -v131, v132, 1.0
	v_fmac_f32_e32 v132, v133, v132
	v_div_scale_f32 v133, vcc, s19, v129, s19
	v_mul_f32_e32 v134, v133, v132
	v_fma_f32 v135, -v131, v134, v133
	v_fmac_f32_e32 v134, v135, v132
	v_fma_f32 v131, -v131, v134, v133
	v_div_fmas_f32 v131, v131, v132, v134
	v_div_fixup_f32 v134, v131, v129, s19
	v_lshlrev_b32_e32 v129, 5, v136
	s_mov_b32 s19, 0x3fbe0
	v_and_or_b32 v129, v129, s19, v155
	s_movk_i32 s19, 0x1800
	v_lshlrev_b32_e32 v129, 1, v129
	v_mad_i64_i32 v[132:133], s[20:21], v136, s19, 0
	v_pk_mul_f32 v[160:161], v[46:47], v[134:135] op_sel_hi:[1,0]
	v_pk_mul_f32 v[164:165], v[44:45], v[134:135] op_sel_hi:[1,0]
	v_pk_mul_f32 v[136:137], v[42:43], v[134:135] op_sel_hi:[1,0]
	v_pk_mul_f32 v[162:163], v[40:41], v[134:135] op_sel_hi:[1,0]
	s_mov_b64 s[20:21], -1
	s_and_b64 vcc, exec, s[44:45]
	v_lshl_add_u64 v[132:133], s[94:95], 0, v[132:133]
	v_lshlrev_b32_e32 v131, 2, v129
	s_cbranch_vccnz .LBB0_789
	global_load_dwordx4 v[166:169], v131, s[72:73] offset:16
	global_load_dwordx4 v[170:173], v131, s[72:73]
	s_add_i32 s19, s22, 0xfffff800
	s_lshr_b32 s19, s19, 6
	s_mul_i32 s20, s19, 0xc0
	s_ashr_i32 s21, s20, 31
	s_waitcnt vmcnt(0)
	v_pk_mul_f32 v[176:177], v[164:165], v[170:171]
	v_pk_mul_f32 v[170:171], v[164:165], v[170:171] op_sel:[1,0] op_sel_hi:[0,1]
	v_add_f32_e32 v135, v170, v171
	v_pk_mul_f32 v[170:171], v[160:161], v[172:173] op_sel:[1,0] op_sel_hi:[0,1]
	v_pk_mul_f32 v[174:175], v[160:161], v[172:173]
	v_add_f32_e32 v159, v170, v171
	v_pk_mul_f32 v[170:171], v[136:137], v[168:169]
	v_pk_mul_f32 v[172:173], v[162:163], v[166:167]
	v_pk_mul_f32 v[166:167], v[162:163], v[166:167] op_sel:[1,0] op_sel_hi:[0,1]
	v_sub_f32_e32 v129, v176, v177
	v_sub_f32_e32 v172, v172, v173
	v_add_f32_e32 v173, v166, v167
	v_sub_f32_e32 v170, v170, v171
	v_pk_mul_f32 v[166:167], v[136:137], v[168:169] op_sel:[1,0] op_sel_hi:[0,1]
	v_sub_f32_e32 v157, v174, v175
	v_add_f32_e32 v169, v166, v167
	v_cvt_pk_bf16_f32 v166, v129, v157
	v_cvt_pk_bf16_f32 v167, v172, v170
	v_lshl_add_u64 v[170:171], s[20:21], 1, v[132:133]
	v_mov_b32_e32 v129, v181
	v_lshl_add_u64 v[170:171], v[170:171], 0, v[128:129]
	s_mov_b64 s[20:21], 0
	v_cvt_pk_bf16_f32 v168, v135, v159
	v_cvt_pk_bf16_f32 v169, v173, v169
	global_store_dwordx2 v[170:171], v[166:167], off offset:256
	global_store_dwordx2 v[170:171], v[168:169], off offset:320

; __device__ __forceinline__ unsigned cvt_pk_bf16(float lo, float hi) { unsigned r; asm volatile("v_cvt_pk_bf16_f32 %0, %1, %2" : "=v"(r) : "v"(lo), "v"(hi)); return r; }
; __device__ __forceinline__ u32x4 pack8(f32x4 a, f32x4 b) { u32x4 w; w.x = cvt_pk_bf16(a[0], a[1]); w.y = cvt_pk_bf16(a[2], a[3]); w.z = cvt_pk_bf16(b[0], b[1]); w.w = cvt_pk_bf16(b[2], b[3]); return w; }
;     __device__ __forceinline__ void operator()(const f32x4 (&acc)[2][2][4][2], const pg8::Unit& u, int wr, int wc, int fr, int fq) const {
;     ...
;                 for (int m = 0; m < 4; ++m) { const int row = row0 + ai * 128 + m * 16;
;                     const f32x4 pa = *(const f32x4*)(f0 + (size_t)row * 16), pb = *(const f32x4*)(f0 + (size_t)row * 16 + 4);
;                     const float ssq = ((pa[0] + pa[1]) + (pa[2] + pa[3])) + ((pb[0] + pb[1]) + (pb[2] + pb[3]));
;                     const float sc = qsc / sqrtf(ssq * (1.0f / 512.0f) + 1e-6f);
; #pragma unroll
;                     for (int bj = 0; bj < 2; ++bj) { const int col = colb + bj * 128; const f32x4 v0 = acc[ai][bj][m][0] * sc, v1 = acc[ai][bj][m][1] * sc;
;                         if (pn < 8) { const int h = col >> 7, d = col & 127; *(u32x4*)(o0 + (size_t)row * 3072 + h * 192 + d) = pack8(v0, v1); }
;                         else { const int j = col - 2048, h = j >> 6, i0 = (j & 63) >> 1, pos = row & 8191;
;                             const f32x4 t0 = *(const f32x4*)(tab + ((size_t)pos * 32 + i0) * 2), t1 = *(const f32x4*)(tab + ((size_t)pos * 32 + i0) * 2 + 4);
;                             const float a0 = v0[0] * t0[0] - v0[1] * t0[1], b0 = v0[1] * t0[0] + v0[0] * t0[1];
;                             const float a1 = v0[2] * t0[2] - v0[3] * t0[3], b1 = v0[3] * t0[2] + v0[2] * t0[3];
;                             const float a2 = v1[0] * t1[0] - v1[1] * t1[1], b2 = v1[1] * t1[0] + v1[0] * t1[1];
;                             const float a3 = v1[2] * t1[2] - v1[3] * t1[3], b3 = v1[3] * t1[2] + v1[2] * t1[3];
;                             u32x2 wa, wb; wa.x = cvt_pk_bf16(a0, a1); wa.y = cvt_pk_bf16(a2, a3); wb.x = cvt_pk_bf16(b0, b1); wb.y = cvt_pk_bf16(b2, b3);
;                             bf16_t* qp = o0 + (size_t)row * 3072 + h * 192 + 128 + i0; *(u32x2*)qp = wa; *(u32x2*)(qp + 32) = wb; } }
.LBB0_795:
	v_add_u32_e32 v136, 0xa0, v158
	v_ashrrev_i32_e32 v137, 31, v136
	v_lshlrev_b64 v[132:133], 6, v[136:137]
	s_mov_b32 s19, 0x3dd53b94
	s_waitcnt vmcnt(10)
	v_mov_b32_e32 v132, v224
	v_mov_b32_e32 v133, v225
	v_mov_b32_e32 v134, v226
	v_mov_b32_e32 v135, v227
	v_mov_b32_e32 v160, v228
	v_mov_b32_e32 v161, v229
	v_mov_b32_e32 v162, v230
	v_mov_b32_e32 v163, v231
	v_mov_b32_e32 v164, v132
	v_mov_b32_e32 v165, v160
	v_mov_b32_e32 v160, v133
	v_pk_add_f32 v[132:133], v[164:165], v[160:161]
	v_mov_b32_e32 v160, v134
	v_mov_b32_e32 v161, v162
	v_mov_b32_e32 v162, v135
	v_pk_add_f32 v[134:135], v[160:161], v[162:163]
	s_nop 0
	v_pk_add_f32 v[132:133], v[132:133], v[134:135]
	s_nop 0
	v_add_f32_e32 v129, v132, v133
	v_fmamk_f32 v129, v129, 0x3b000000, v219
	v_cmp_gt_f32_e32 vcc, s86, v129
	v_mul_f32_e32 v131, 0x4f800000, v129
	s_nop 0
	v_cndmask_b32_e32 v129, v129, v131, vcc
	v_sqrt_f32_e32 v131, v129
	s_nop 0
	v_add_u32_e32 v132, -1, v131
	v_fma_f32 v133, -v132, v131, v129
	v_cmp_ge_f32_e64 s[46:47], 0, v133
	v_add_u32_e32 v133, 1, v131
	s_nop 0
	v_cndmask_b32_e64 v132, v131, v132, s[46:47]
	v_fma_f32 v131, -v133, v131, v129
	v_cmp_lt_f32_e64 s[46:47], 0, v131
	s_nop 1
	v_cndmask_b32_e64 v131, v132, v133, s[46:47]
	v_mul_f32_e32 v132, 0x37800000, v131
	v_cndmask_b32_e32 v131, v131, v132, vcc
	v_cmp_class_f32_e32 vcc, v129, v215
	s_nop 1
	v_cndmask_b32_e32 v129, v131, v129, vcc
	v_div_scale_f32 v131, s[20:21], v129, v129, s19
	v_rcp_f32_e32 v132, v131
	s_nop 0
	v_fma_f32 v133, -v131, v132, 1.0
	v_fmac_f32_e32 v132, v133, v132
	v_div_scale_f32 v133, vcc, s19, v129, s19
	v_mul_f32_e32 v134, v133, v132
	v_fma_f32 v135, -v131, v134, v133
	v_fmac_f32_e32 v134, v135, v132
	v_fma_f32 v131, -v131, v134, v133
	v_div_fmas_f32 v131, v131, v132, v134
	v_div_fixup_f32 v134, v131, v129, s19
	v_lshlrev_b32_e32 v129, 5, v136
	s_mov_b32 s19, 0x3fde0
	v_and_or_b32 v129, v129, s19, v155
	s_movk_i32 s19, 0x1800
	v_lshlrev_b32_e32 v129, 1, v129
	v_mad_i64_i32 v[132:133], s[20:21], v136, s19, 0
	v_pk_mul_f32 v[160:161], v[30:31], v[134:135] op_sel_hi:[1,0]
	v_pk_mul_f32 v[164:165], v[28:29], v[134:135] op_sel_hi:[1,0]
	v_pk_mul_f32 v[136:137], v[26:27], v[134:135] op_sel_hi:[1,0]
	v_pk_mul_f32 v[162:163], v[24:25], v[134:135] op_sel_hi:[1,0]
	s_mov_b64 s[20:21], -1
	s_and_b64 vcc, exec, s[44:45]
	v_lshl_add_u64 v[132:133], s[94:95], 0, v[132:133]
	v_lshlrev_b32_e32 v131, 2, v129
	s_cbranch_vccnz .LBB0_797
	global_load_dwordx4 v[166:169], v131, s[72:73] offset:16
	global_load_dwordx4 v[170:173], v131, s[72:73]
	s_add_i32 s19, s22, 0xfffff800
	s_lshr_b32 s19, s19, 6
	s_mul_i32 s20, s19, 0xc0
	s_ashr_i32 s21, s20, 31
	s_waitcnt vmcnt(0)
	v_pk_mul_f32 v[176:177], v[164:165], v[170:171]
	v_pk_mul_f32 v[170:171], v[164:165], v[170:171] op_sel:[1,0] op_sel_hi:[0,1]
	v_add_f32_e32 v135, v170, v171
	v_pk_mul_f32 v[170:171], v[160:161], v[172:173] op_sel:[1,0] op_sel_hi:[0,1]
	v_pk_mul_f32 v[174:175], v[160:161], v[172:173]
	v_add_f32_e32 v159, v170, v171
	v_pk_mul_f32 v[170:171], v[136:137], v[168:169]
	v_pk_mul_f32 v[172:173], v[162:163], v[166:167]
	v_pk_mul_f32 v[166:167], v[162:163], v[166:167] op_sel:[1,0] op_sel_hi:[0,1]
	v_sub_f32_e32 v129, v176, v177
	v_sub_f32_e32 v172, v172, v173
	v_add_f32_e32 v173, v166, v167
	v_sub_f32_e32 v170, v170, v171
	v_pk_mul_f32 v[166:167], v[136:137], v[168:169] op_sel:[1,0] op_sel_hi:[0,1]
	v_sub_f32_e32 v157, v174, v175
	v_add_f32_e32 v169, v166, v167
	v_cvt_pk_bf16_f32 v166, v129, v157
	v_cvt_pk_bf16_f32 v167, v172, v170
	v_lshl_add_u64 v[170:171], s[20:21], 1, v[132:133]
	v_mov_b32_e32 v129, v181
	v_lshl_add_u64 v[170:171], v[170:171], 0, v[128:129]
	s_mov_b64 s[20:21], 0
	v_cvt_pk_bf16_f32 v168, v135, v159
	v_cvt_pk_bf16_f32 v169, v173, v169
	global_store_dwordx2 v[170:171], v[166:167], off offset:256
	global_store_dwordx2 v[170:171], v[168:169], off offset:320

; __device__ __forceinline__ unsigned cvt_pk_bf16(float lo, float hi) { unsigned r; asm volatile("v_cvt_pk_bf16_f32 %0, %1, %2" : "=v"(r) : "v"(lo), "v"(hi)); return r; }
; __device__ __forceinline__ u32x4 pack8(f32x4 a, f32x4 b) { u32x4 w; w.x = cvt_pk_bf16(a[0], a[1]); w.y = cvt_pk_bf16(a[2], a[3]); w.z = cvt_pk_bf16(b[0], b[1]); w.w = cvt_pk_bf16(b[2], b[3]); return w; }
;     __device__ __forceinline__ void operator()(const f32x4 (&acc)[2][2][4][2], const pg8::Unit& u, int wr, int wc, int fr, int fq) const {
;     ...
;                 for (int m = 0; m < 4; ++m) { const int row = row0 + ai * 128 + m * 16;
;                     const f32x4 pa = *(const f32x4*)(f0 + (size_t)row * 16), pb = *(const f32x4*)(f0 + (size_t)row * 16 + 4);
;                     const float ssq = ((pa[0] + pa[1]) + (pa[2] + pa[3])) + ((pb[0] + pb[1]) + (pb[2] + pb[3]));
;                     const float sc = qsc / sqrtf(ssq * (1.0f / 512.0f) + 1e-6f);
; #pragma unroll
;                     for (int bj = 0; bj < 2; ++bj) { const int col = colb + bj * 128; const f32x4 v0 = acc[ai][bj][m][0] * sc, v1 = acc[ai][bj][m][1] * sc;
;                         if (pn < 8) { const int h = col >> 7, d = col & 127; *(u32x4*)(o0 + (size_t)row * 3072 + h * 192 + d) = pack8(v0, v1); }
;                         else { const int j = col - 2048, h = j >> 6, i0 = (j & 63) >> 1, pos = row & 8191;
;                             const f32x4 t0 = *(const f32x4*)(tab + ((size_t)pos * 32 + i0) * 2), t1 = *(const f32x4*)(tab + ((size_t)pos * 32 + i0) * 2 + 4);
;                             const float a0 = v0[0] * t0[0] - v0[1] * t0[1], b0 = v0[1] * t0[0] + v0[0] * t0[1];
;                             const float a1 = v0[2] * t0[2] - v0[3] * t0[3], b1 = v0[3] * t0[2] + v0[2] * t0[3];
;                             const float a2 = v1[0] * t1[0] - v1[1] * t1[1], b2 = v1[1] * t1[0] + v1[0] * t1[1];
;                             const float a3 = v1[2] * t1[2] - v1[3] * t1[3], b3 = v1[3] * t1[2] + v1[2] * t1[3];
;                             u32x2 wa, wb; wa.x = cvt_pk_bf16(a0, a1); wa.y = cvt_pk_bf16(a2, a3); wb.x = cvt_pk_bf16(b0, b1); wb.y = cvt_pk_bf16(b2, b3);
;                             bf16_t* qp = o0 + (size_t)row * 3072 + h * 192 + 128 + i0; *(u32x2*)qp = wa; *(u32x2*)(qp + 32) = wb; } }
.LBB0_803:
	v_add_u32_e32 v136, 0xb0, v158
	v_ashrrev_i32_e32 v137, 31, v136
	v_lshlrev_b64 v[132:133], 6, v[136:137]
	s_mov_b32 s19, 0x3dd53b94
	s_waitcnt vmcnt(8)
	v_mov_b32_e32 v132, v232
	v_mov_b32_e32 v133, v233
	v_mov_b32_e32 v134, v234
	v_mov_b32_e32 v135, v235
	v_mov_b32_e32 v160, v236
	v_mov_b32_e32 v161, v237
	v_mov_b32_e32 v162, v238
	v_mov_b32_e32 v163, v239
	v_mov_b32_e32 v164, v132
	v_mov_b32_e32 v165, v160
	v_mov_b32_e32 v160, v133
	v_pk_add_f32 v[132:133], v[164:165], v[160:161]
	v_mov_b32_e32 v160, v134
	v_mov_b32_e32 v161, v162
	v_mov_b32_e32 v162, v135
	v_pk_add_f32 v[134:135], v[160:161], v[162:163]
	s_nop 0
	v_pk_add_f32 v[132:133], v[132:133], v[134:135]
	s_nop 0
	v_add_f32_e32 v129, v132, v133
	v_fmamk_f32 v129, v129, 0x3b000000, v219
	v_cmp_gt_f32_e32 vcc, s86, v129
	v_mul_f32_e32 v131, 0x4f800000, v129
	s_nop 0
	v_cndmask_b32_e32 v129, v129, v131, vcc
	v_sqrt_f32_e32 v131, v129
	s_nop 0
	v_add_u32_e32 v132, -1, v131
	v_fma_f32 v133, -v132, v131, v129
	v_cmp_ge_f32_e64 s[46:47], 0, v133
	v_add_u32_e32 v133, 1, v131
	s_nop 0
	v_cndmask_b32_e64 v132, v131, v132, s[46:47]
	v_fma_f32 v131, -v133, v131, v129
	v_cmp_lt_f32_e64 s[46:47], 0, v131
	s_nop 1
	v_cndmask_b32_e64 v131, v132, v133, s[46:47]
	v_mul_f32_e32 v132, 0x37800000, v131
	v_cndmask_b32_e32 v131, v131, v132, vcc
	v_cmp_class_f32_e32 vcc, v129, v215
	s_nop 1
	v_cndmask_b32_e32 v129, v131, v129, vcc
	v_div_scale_f32 v131, s[20:21], v129, v129, s19
	v_rcp_f32_e32 v132, v131
	s_nop 0
	v_fma_f32 v133, -v131, v132, 1.0
	v_fmac_f32_e32 v132, v133, v132
	v_div_scale_f32 v133, vcc, s19, v129, s19
	v_mul_f32_e32 v134, v133, v132
	v_fma_f32 v135, -v131, v134, v133
	v_fmac_f32_e32 v134, v135, v132
	v_fma_f32 v131, -v131, v134, v133
	v_div_fmas_f32 v131, v131, v132, v134
	v_div_fixup_f32 v134, v131, v129, s19
	v_lshlrev_b32_e32 v129, 5, v136
	s_mov_b32 s19, 0x3ffe0
	v_and_or_b32 v129, v129, s19, v155
	s_movk_i32 s19, 0x1800
	v_lshlrev_b32_e32 v129, 1, v129
	v_mad_i64_i32 v[132:133], s[20:21], v136, s19, 0
	v_pk_mul_f32 v[160:161], v[14:15], v[134:135] op_sel_hi:[1,0]
	v_pk_mul_f32 v[164:165], v[12:13], v[134:135] op_sel_hi:[1,0]
	v_pk_mul_f32 v[136:137], v[10:11], v[134:135] op_sel_hi:[1,0]
	v_pk_mul_f32 v[162:163], v[8:9], v[134:135] op_sel_hi:[1,0]
	s_mov_b64 s[20:21], -1
	s_and_b64 vcc, exec, s[44:45]
	v_lshl_add_u64 v[132:133], s[94:95], 0, v[132:133]
	v_lshlrev_b32_e32 v131, 2, v129
	s_cbranch_vccnz .LBB0_805
	global_load_dwordx4 v[166:169], v131, s[72:73] offset:16
	global_load_dwordx4 v[170:173], v131, s[72:73]
	s_add_i32 s19, s22, 0xfffff800
	s_lshr_b32 s19, s19, 6
	s_mul_i32 s20, s19, 0xc0
	s_ashr_i32 s21, s20, 31
	s_waitcnt vmcnt(0)
	v_pk_mul_f32 v[176:177], v[164:165], v[170:171]
	v_pk_mul_f32 v[170:171], v[164:165], v[170:171] op_sel:[1,0] op_sel_hi:[0,1]
	v_add_f32_e32 v135, v170, v171
	v_pk_mul_f32 v[170:171], v[160:161], v[172:173] op_sel:[1,0] op_sel_hi:[0,1]
	v_pk_mul_f32 v[174:175], v[160:161], v[172:173]
	v_add_f32_e32 v157, v170, v171
	v_pk_mul_f32 v[170:171], v[136:137], v[168:169]
	v_pk_mul_f32 v[172:173], v[162:163], v[166:167]
	v_pk_mul_f32 v[166:167], v[162:163], v[166:167] op_sel:[1,0] op_sel_hi:[0,1]
	v_sub_f32_e32 v129, v176, v177
	v_sub_f32_e32 v159, v172, v173
	v_add_f32_e32 v172, v166, v167
	v_sub_f32_e32 v170, v170, v171
	v_pk_mul_f32 v[166:167], v[136:137], v[168:169] op_sel:[1,0] op_sel_hi:[0,1]
	v_sub_f32_e32 v155, v174, v175
	v_add_f32_e32 v169, v166, v167
	v_cvt_pk_bf16_f32 v166, v129, v155
	v_cvt_pk_bf16_f32 v167, v159, v170
	v_lshl_add_u64 v[170:171], s[20:21], 1, v[132:133]
	v_mov_b32_e32 v129, v181
	v_lshl_add_u64 v[170:171], v[170:171], 0, v[128:129]
	s_mov_b64 s[20:21], 0
	v_cvt_pk_bf16_f32 v168, v135, v157
	v_cvt_pk_bf16_f32 v169, v172, v169
	global_store_dwordx2 v[170:171], v[166:167], off offset:256
	global_store_dwordx2 v[170:171], v[168:169], off offset:320
